# merge GEMM epilogue: 16 gate loads issued together, stores no longer waited on between steps
# speedup vs baseline: 1.0122x; 1.0008x over previous
; __device__ __forceinline__ unsigned cvt_pk_bf16(float lo, float hi) { unsigned r; asm volatile("v_cvt_pk_bf16_f32 %0, %1, %2" : "=v"(r) : "v"(lo), "v"(hi)); return r; }
;     static __device__ __forceinline__ float gv(unsigned long long gw, int i) { return __uint_as_float((unsigned)((gw >> (16 * i)) & 0xffffull) << 16); }
;     __device__ __forceinline__ void operator()(const f32x4 (&acc)[2][2][4][2], const Unit& u, int wr, int wc, int fr, int fq) const {
;         const int col0 = u.pn * BM + wc * 32 + 4 * fq;
; #pragma unroll
;         for (int ai = 0; ai < 1; ++ai)
; #pragma unroll
;             for (int m = 0; m < 4; ++m) { const size_t row = (size_t)(u.pm * HALF + wr * 64 + m * 16 + fr);
; #pragma unroll
;                 for (int bj = 0; bj < 2; ++bj)
; #pragma unroll
;                     for (int n = 0; n < 2; ++n) { const int c = col0 + bj * HALF + n * 16;
;                         const unsigned long long gw = *(const unsigned long long*)(G + row * ldg + c + 2048);
;                         f32x4 v;
; #pragma unroll
;                         for (int i = 0; i < 4; ++i) v[i] = acc[ai][bj][m][n][i] * gv(gw, i);
;                         *(unsigned long long*)(Yb + row * ldc + c) = (unsigned long long)cvt_pk_bf16(v[0], v[1]) | ((unsigned long long)cvt_pk_bf16(v[2], v[3]) << 32); } }
;     }
.LBB0_82:
	v_add_co_u32_e32 v90, vcc, 0x1000, v90
	s_movk_i32 s0, 0x1000
	s_nop 0
	v_addc_co_u32_e32 v91, vcc, 0, v91, vcc
	s_mov_b64 s[16:17], -1
	global_load_dwordx2 v[176:177], v[90:91], off
	global_load_dwordx2 v[178:179], v[90:91], off offset:32
	global_load_dwordx2 v[180:181], v[90:91], off offset:256
	global_load_dwordx2 v[182:183], v[90:91], off offset:288
	v_add_co_u32_e32 v166, vcc, s0, v86
	s_nop 1
	v_addc_co_u32_e32 v167, vcc, 0, v87, vcc
	global_load_dwordx2 v[184:185], v[166:167], off
	global_load_dwordx2 v[186:187], v[166:167], off offset:32
	global_load_dwordx2 v[188:189], v[166:167], off offset:256
	global_load_dwordx2 v[190:191], v[166:167], off offset:288
	v_add_co_u32_e32 v166, vcc, s0, v82
	s_nop 1
	v_addc_co_u32_e32 v167, vcc, 0, v83, vcc
	global_load_dwordx2 v[192:193], v[166:167], off
	global_load_dwordx2 v[194:195], v[166:167], off offset:32
	global_load_dwordx2 v[198:199], v[166:167], off offset:256
	global_load_dwordx2 v[200:201], v[166:167], off offset:288
	v_add_co_u32_e32 v166, vcc, s0, v78
	s_nop 1
	v_addc_co_u32_e32 v167, vcc, 0, v79, vcc
	global_load_dwordx2 v[202:203], v[166:167], off
	global_load_dwordx2 v[204:205], v[166:167], off offset:32
	global_load_dwordx2 v[206:207], v[166:167], off offset:256
	global_load_dwordx2 v[208:209], v[166:167], off offset:288
	v_lshlrev_b64 v[96:97], 11, v[88:89]
	v_lshl_add_u64 v[96:97], s[8:9], 0, v[96:97]
	v_lshl_add_u64 v[96:97], v[96:97], 0, v[76:77]
	v_lshlrev_b64 v[98:99], 11, v[84:85]
	v_lshl_add_u64 v[98:99], s[8:9], 0, v[98:99]
	v_lshl_add_u64 v[98:99], v[98:99], 0, v[76:77]
	v_lshlrev_b64 v[106:107], 11, v[80:81]
	v_lshl_add_u64 v[106:107], s[8:9], 0, v[106:107]
	v_lshl_add_u64 v[106:107], v[106:107], 0, v[76:77]
	v_lshlrev_b64 v[108:109], 11, v[74:75]
	v_lshl_add_u64 v[108:109], s[8:9], 0, v[108:109]
	v_lshl_add_u64 v[108:109], v[108:109], 0, v[76:77]
	s_waitcnt vmcnt(15)
	v_lshlrev_b32_e32 v105, 16, v176
	v_mul_f32_e32 v62, v62, v105
	v_and_b32_e32 v105, 0xffff0000, v176
	v_mul_f32_e32 v63, v63, v105
	v_lshlrev_b32_e32 v105, 16, v177
	v_mul_f32_e32 v64, v64, v105
	v_and_b32_e32 v105, 0xffff0000, v177
	v_mul_f32_e32 v65, v65, v105
	v_cvt_pk_bf16_f32 v62, v62, v63
	v_cvt_pk_bf16_f32 v63, v64, v65
	global_store_dwordx2 v[96:97], v[62:63], off
	s_waitcnt vmcnt(15)
	v_lshlrev_b32_e32 v105, 16, v178
	v_mul_f32_e32 v58, v58, v105
	v_and_b32_e32 v105, 0xffff0000, v178
	v_mul_f32_e32 v59, v59, v105
	v_lshlrev_b32_e32 v105, 16, v179
	v_mul_f32_e32 v60, v60, v105
	v_and_b32_e32 v105, 0xffff0000, v179
	v_mul_f32_e32 v61, v61, v105
	v_cvt_pk_bf16_f32 v58, v58, v59
	v_cvt_pk_bf16_f32 v59, v60, v61
	global_store_dwordx2 v[96:97], v[58:59], off offset:32
	s_waitcnt vmcnt(15)
	v_lshlrev_b32_e32 v105, 16, v180
	v_mul_f32_e32 v54, v54, v105
	v_and_b32_e32 v105, 0xffff0000, v180
	v_mul_f32_e32 v55, v55, v105
	v_lshlrev_b32_e32 v105, 16, v181
	v_mul_f32_e32 v56, v56, v105
	v_and_b32_e32 v105, 0xffff0000, v181
	v_mul_f32_e32 v57, v57, v105
	v_cvt_pk_bf16_f32 v54, v54, v55
	v_cvt_pk_bf16_f32 v55, v56, v57
	global_store_dwordx2 v[96:97], v[54:55], off offset:256
	s_waitcnt vmcnt(15)
	v_lshlrev_b32_e32 v105, 16, v182
	v_mul_f32_e32 v50, v50, v105
	v_and_b32_e32 v105, 0xffff0000, v182
	v_mul_f32_e32 v51, v51, v105
	v_lshlrev_b32_e32 v105, 16, v183
	v_mul_f32_e32 v52, v52, v105
	v_and_b32_e32 v105, 0xffff0000, v183
	v_mul_f32_e32 v53, v53, v105
	v_cvt_pk_bf16_f32 v50, v50, v51
	v_cvt_pk_bf16_f32 v51, v52, v53
	global_store_dwordx2 v[96:97], v[50:51], off offset:288
	s_waitcnt vmcnt(15)
	v_lshlrev_b32_e32 v105, 16, v184
	v_mul_f32_e32 v46, v46, v105
	v_and_b32_e32 v105, 0xffff0000, v184
	v_mul_f32_e32 v47, v47, v105
	v_lshlrev_b32_e32 v105, 16, v185
	v_mul_f32_e32 v48, v48, v105
	v_and_b32_e32 v105, 0xffff0000, v185
	v_mul_f32_e32 v49, v49, v105
	v_cvt_pk_bf16_f32 v46, v46, v47
	v_cvt_pk_bf16_f32 v47, v48, v49
	global_store_dwordx2 v[98:99], v[46:47], off
	s_waitcnt vmcnt(15)
	v_lshlrev_b32_e32 v105, 16, v186
	v_mul_f32_e32 v42, v42, v105
	v_and_b32_e32 v105, 0xffff0000, v186
	v_mul_f32_e32 v43, v43, v105
	v_lshlrev_b32_e32 v105, 16, v187
	v_mul_f32_e32 v44, v44, v105
	v_and_b32_e32 v105, 0xffff0000, v187
	v_mul_f32_e32 v45, v45, v105
	v_cvt_pk_bf16_f32 v42, v42, v43
	v_cvt_pk_bf16_f32 v43, v44, v45
	global_store_dwordx2 v[98:99], v[42:43], off offset:32
	s_waitcnt vmcnt(15)
; __device__ __forceinline__ unsigned cvt_pk_bf16(float lo, float hi) { unsigned r; asm volatile("v_cvt_pk_bf16_f32 %0, %1, %2" : "=v"(r) : "v"(lo), "v"(hi)); return r; }
;     static __device__ __forceinline__ float gv(unsigned long long gw, int i) { return __uint_as_float((unsigned)((gw >> (16 * i)) & 0xffffull) << 16); }
; #define PG8_BAR __builtin_amdgcn_s_barrier()
;     __device__ __forceinline__ void operator()(const f32x4 (&acc)[2][2][4][2], const Unit& u, int wr, int wc, int fr, int fq) const {
;     ...
;             for (int m = 0; m < 4; ++m) { const size_t row = (size_t)(u.pm * HALF + wr * 64 + m * 16 + fr);
; #pragma unroll
;                 for (int bj = 0; bj < 2; ++bj)
; #pragma unroll
;                     for (int n = 0; n < 2; ++n) { const int c = col0 + bj * HALF + n * 16;
;                         const unsigned long long gw = *(const unsigned long long*)(G + row * ldg + c + 2048);
;                         f32x4 v;
; #pragma unroll
;                         for (int i = 0; i < 4; ++i) v[i] = acc[ai][bj][m][n][i] * gv(gw, i);
;                         *(unsigned long long*)(Yb + row * ldc + c) = (unsigned long long)cvt_pk_bf16(v[0], v[1]) | ((unsigned long long)cvt_pk_bf16(v[2], v[3]) << 32); } }
;     }
; template <class Epi, class Sched, bool ALIGN_EPI = false, bool SP2 = false, bool HALFM = false>
; __device__ __forceinline__ void gemm_phase(PG8_LAS unsigned char* lds, const Gemm g, const Sched& S, const Epi& E, const int tid_in) {
;     ...
;         if constexpr (ALIGN_EPI) { if (wr == 0) PG8_BAR; }
;         if constexpr (!Epi::AFTER_DRAIN) { E(acc, cur, wr, wc, fr, fq); S.done(cur); }
;         if (!has_next) break;
; #pragma unroll
;         for (int a = 0; a < 2; ++a)
; #pragma unroll
;             for (int b = 0; b < 2; ++b)
; #pragma unroll
;                 for (int m = 0; m < 4; ++m)
; #pragma unroll
;                     for (int n = 0; n < 2; ++n) acc[a][b][m][n] = (f32x4){0.f, 0.f, 0.f, 0.f};
;         cur = nxt; cA = nA; cB = nB; ++ui;
;         if constexpr (ALIGN_EPI) { if (wr == 1) PG8_BAR; }
	v_lshlrev_b32_e32 v105, 16, v188
	v_mul_f32_e32 v38, v38, v105
	v_and_b32_e32 v105, 0xffff0000, v188
	v_mul_f32_e32 v39, v39, v105
	v_lshlrev_b32_e32 v105, 16, v189
	v_mul_f32_e32 v40, v40, v105
	v_and_b32_e32 v105, 0xffff0000, v189
	v_mul_f32_e32 v41, v41, v105
	v_cvt_pk_bf16_f32 v38, v38, v39
	v_cvt_pk_bf16_f32 v39, v40, v41
	global_store_dwordx2 v[98:99], v[38:39], off offset:256
	s_waitcnt vmcnt(15)
	v_lshlrev_b32_e32 v105, 16, v190
	v_mul_f32_e32 v34, v34, v105
	v_and_b32_e32 v105, 0xffff0000, v190
	v_mul_f32_e32 v35, v35, v105
	v_lshlrev_b32_e32 v105, 16, v191
	v_mul_f32_e32 v36, v36, v105
	v_and_b32_e32 v105, 0xffff0000, v191
	v_mul_f32_e32 v37, v37, v105
	v_cvt_pk_bf16_f32 v34, v34, v35
	v_cvt_pk_bf16_f32 v35, v36, v37
	global_store_dwordx2 v[98:99], v[34:35], off offset:288
	s_waitcnt vmcnt(15)
	v_lshlrev_b32_e32 v105, 16, v192
	v_mul_f32_e32 v30, v30, v105
	v_and_b32_e32 v105, 0xffff0000, v192
	v_mul_f32_e32 v31, v31, v105
	v_lshlrev_b32_e32 v105, 16, v193
	v_mul_f32_e32 v32, v32, v105
	v_and_b32_e32 v105, 0xffff0000, v193
	v_mul_f32_e32 v33, v33, v105
	v_cvt_pk_bf16_f32 v30, v30, v31
	v_cvt_pk_bf16_f32 v31, v32, v33
	global_store_dwordx2 v[106:107], v[30:31], off
	s_waitcnt vmcnt(15)
	v_lshlrev_b32_e32 v105, 16, v194
	v_mul_f32_e32 v26, v26, v105
	v_and_b32_e32 v105, 0xffff0000, v194
	v_mul_f32_e32 v27, v27, v105
	v_lshlrev_b32_e32 v105, 16, v195
	v_mul_f32_e32 v28, v28, v105
	v_and_b32_e32 v105, 0xffff0000, v195
	v_mul_f32_e32 v29, v29, v105
	v_cvt_pk_bf16_f32 v26, v26, v27
	v_cvt_pk_bf16_f32 v27, v28, v29
	global_store_dwordx2 v[106:107], v[26:27], off offset:32
	s_waitcnt vmcnt(15)
	v_lshlrev_b32_e32 v105, 16, v198
	v_mul_f32_e32 v22, v22, v105
	v_and_b32_e32 v105, 0xffff0000, v198
	v_mul_f32_e32 v23, v23, v105
	v_lshlrev_b32_e32 v105, 16, v199
	v_mul_f32_e32 v24, v24, v105
	v_and_b32_e32 v105, 0xffff0000, v199
	v_mul_f32_e32 v25, v25, v105
	v_cvt_pk_bf16_f32 v22, v22, v23
	v_cvt_pk_bf16_f32 v23, v24, v25
	global_store_dwordx2 v[106:107], v[22:23], off offset:256
	s_waitcnt vmcnt(15)
	v_lshlrev_b32_e32 v105, 16, v200
	v_mul_f32_e32 v18, v18, v105
	v_and_b32_e32 v105, 0xffff0000, v200
	v_mul_f32_e32 v19, v19, v105
	v_lshlrev_b32_e32 v105, 16, v201
	v_mul_f32_e32 v20, v20, v105
	v_and_b32_e32 v105, 0xffff0000, v201
	v_mul_f32_e32 v21, v21, v105
	v_cvt_pk_bf16_f32 v18, v18, v19
	v_cvt_pk_bf16_f32 v19, v20, v21
	global_store_dwordx2 v[106:107], v[18:19], off offset:288
	s_waitcnt vmcnt(15)
	v_lshlrev_b32_e32 v105, 16, v202
	v_mul_f32_e32 v14, v14, v105
	v_and_b32_e32 v105, 0xffff0000, v202
	v_mul_f32_e32 v15, v15, v105
	v_lshlrev_b32_e32 v105, 16, v203
	v_mul_f32_e32 v16, v16, v105
	v_and_b32_e32 v105, 0xffff0000, v203
	v_mul_f32_e32 v17, v17, v105
	v_cvt_pk_bf16_f32 v14, v14, v15
	v_cvt_pk_bf16_f32 v15, v16, v17
	global_store_dwordx2 v[108:109], v[14:15], off
	s_waitcnt vmcnt(15)
	v_lshlrev_b32_e32 v105, 16, v204
	v_mul_f32_e32 v10, v10, v105
	v_and_b32_e32 v105, 0xffff0000, v204
	v_mul_f32_e32 v11, v11, v105
	v_lshlrev_b32_e32 v105, 16, v205
	v_mul_f32_e32 v12, v12, v105
	v_and_b32_e32 v105, 0xffff0000, v205
	v_mul_f32_e32 v13, v13, v105
	v_cvt_pk_bf16_f32 v10, v10, v11
	v_cvt_pk_bf16_f32 v11, v12, v13
	global_store_dwordx2 v[108:109], v[10:11], off offset:32
	s_waitcnt vmcnt(15)
	v_lshlrev_b32_e32 v105, 16, v206
	v_mul_f32_e32 v6, v6, v105
	v_and_b32_e32 v105, 0xffff0000, v206
	v_mul_f32_e32 v7, v7, v105
	v_lshlrev_b32_e32 v105, 16, v207
	v_mul_f32_e32 v8, v8, v105
	v_and_b32_e32 v105, 0xffff0000, v207
	v_mul_f32_e32 v9, v9, v105
	v_cvt_pk_bf16_f32 v6, v6, v7
	v_cvt_pk_bf16_f32 v7, v8, v9
	global_store_dwordx2 v[108:109], v[6:7], off offset:256
	s_waitcnt vmcnt(15)
	v_lshlrev_b32_e32 v105, 16, v208
	v_mul_f32_e32 v2, v2, v105
	v_and_b32_e32 v105, 0xffff0000, v208
	v_mul_f32_e32 v3, v3, v105
	v_lshlrev_b32_e32 v105, 16, v209
	v_mul_f32_e32 v4, v4, v105
	v_and_b32_e32 v105, 0xffff0000, v209
	v_mul_f32_e32 v5, v5, v105
	v_cvt_pk_bf16_f32 v2, v2, v3
	v_cvt_pk_bf16_f32 v3, v4, v5
	global_store_dwordx2 v[108:109], v[2:3], off offset:288
	s_and_b64 vcc, exec, s[4:5]
	s_cbranch_vccnz .LBB0_59
	s_andn2_b64 vcc, exec, s[2:3]
	s_cbranch_vccnz .LBB0_58
	s_barrier
	s_branch .LBB0_58
